# scan state update: all 10 LDS operand reads (ak, dc, 8 VT tiles) issued up front, 8 MFMAs back to back, then the 8 bf16 state write-backs (was 8 serialized read-wait-MFMA-convert-write steps)
# speedup vs baseline: 1.0126x; 1.0006x over previous
.LBB0_666:
	s_waitcnt lgkmcnt(0)
	s_barrier
	ds_read_b128 v[128:131], v100 offset:36352
	v_add_u32_e32 v127, v81, v56
	ds_read_b128 v[132:135], v127
	ds_read_b128 v[136:139], v127 offset:1280
	ds_read_b128 v[196:199], v100 offset:26112
	ds_read_b128 v[200:203], v82
	ds_read_b128 v[204:207], v101 offset:36352
	ds_read_b128 v[208:211], v102 offset:36352
	ds_read_b128 v[212:215], v102 offset:37632
	ds_read_b128 v[216:219], v102 offset:38912
	ds_read_b128 v[220:223], v102 offset:40192
	ds_read_b128 v[160:163], v102 offset:41472
	ds_read_b128 v[164:167], v102 offset:42752
	ds_read_b128 v[176:179], v102 offset:44032
	v_add_u32_e32 v127, v83, v80
	s_add_i32 s68, s68, 1
	s_add_i32 s0, s81, s68
	s_waitcnt lgkmcnt(11)
	v_mfma_f32_16x16x32_bf16 v[40:43], v[128:131], v[132:135], v[40:43]
	s_add_i32 s0, s0, -1
	v_subrev_u32_e32 v108, 32, v108
	v_add_u32_e32 v107, 32, v107
	s_waitcnt lgkmcnt(10)
	v_mfma_f32_16x16x32_bf16 v[44:47], v[128:131], v[136:139], v[44:47]
	s_nop 2
	v_cvt_pk_bf16_f32 v40, v40, v41
	v_cvt_pk_bf16_f32 v41, v42, v43
	v_subrev_u32_e32 v106, 32, v106
	v_add_u32_e32 v63, 32, v63
	s_cmp_ge_i32 s0, s10
	v_cvt_pk_bf16_f32 v42, v44, v45
	v_add_u32_e32 v44, s59, v109
	v_cmp_gt_i32_e32 vcc, s75, v44
	v_cvt_pk_bf16_f32 v43, v46, v47
	v_add_u32_e32 v45, 0xffffff00, v44
	v_cndmask_b32_e32 v46, v228, v229, vcc
	v_cndmask_b32_e32 v47, v45, v44, vcc
	v_add3_u32 v46, s58, v46, v110
	v_cndmask_b32_e64 v46, v46, v47, s[56:57]
	v_cndmask_b32_e32 v45, v71, v69, vcc
	v_cndmask_b32_e32 v44, v70, v68, vcc
	v_ashrrev_i32_e32 v47, 31, v46
	v_lshl_add_u64 v[44:45], v[44:45], 0, v[46:47]
	v_lshlrev_b64 v[44:45], 10, v[44:45]
	v_lshl_add_u64 v[44:45], v[74:75], 0, v[44:45]
	global_store_dwordx2 v[44:45], v[40:41], off
	v_lshl_add_u64 v[40:41], s[72:73], 1, v[44:45]
	global_store_dwordx2 v[40:41], v[42:43], off
	v_subrev_u32_e32 v110, 32, v110
	v_add_u32_e32 v109, 32, v109
	v_add_u32_e32 v184, v83, v85
	v_add_u32_e32 v185, v83, v86
	s_waitcnt lgkmcnt(8)
	v_pk_mul_f32 v[4:5], v[4:5], v[202:203]
	v_pk_mul_f32 v[2:3], v[2:3], v[200:201]
	v_pk_mul_f32 v[8:9], v[8:9], v[202:203]
	v_pk_mul_f32 v[6:7], v[6:7], v[200:201]
	v_mul_f32_e64 v12, v12, v202
	v_mul_f32_e64 v13, v13, v203
	v_pk_mul_f32 v[10:11], v[10:11], v[200:201]
	v_pk_mul_f32 v[16:17], v[16:17], v[202:203]
	v_pk_mul_f32 v[14:15], v[14:15], v[200:201]
	v_pk_mul_f32 v[20:21], v[20:21], v[202:203]
	v_pk_mul_f32 v[18:19], v[18:19], v[200:201]
	v_pk_mul_f32 v[30:31], v[30:31], v[202:203]
	v_mul_f32_e64 v28, v28, v200
	v_mul_f32_e64 v29, v29, v201
	v_pk_mul_f32 v[34:35], v[34:35], v[202:203]
	v_pk_mul_f32 v[32:33], v[32:33], v[200:201]
	v_mul_f32_e64 v24, v24, v202
	v_mul_f32_e64 v25, v25, v203
	v_pk_mul_f32 v[22:23], v[22:23], v[200:201]
	s_waitcnt lgkmcnt(7)
	v_mfma_f32_16x16x32_bf16 v[2:5], v[196:199], v[204:207], v[2:5]
	s_waitcnt lgkmcnt(6)
	v_mfma_f32_16x16x32_bf16 v[6:9], v[196:199], v[208:211], v[6:9]
	s_waitcnt lgkmcnt(5)
	v_mfma_f32_16x16x32_bf16 v[10:13], v[196:199], v[212:215], v[10:13]
	s_waitcnt lgkmcnt(4)
	v_mfma_f32_16x16x32_bf16 v[14:17], v[196:199], v[216:219], v[14:17]
	s_waitcnt lgkmcnt(3)
	v_mfma_f32_16x16x32_bf16 v[18:21], v[196:199], v[220:223], v[18:21]
	s_waitcnt lgkmcnt(2)
	v_mfma_f32_16x16x32_bf16 v[28:31], v[196:199], v[160:163], v[28:31]
	s_waitcnt lgkmcnt(1)
	v_mfma_f32_16x16x32_bf16 v[32:35], v[196:199], v[164:167], v[32:35]
	s_waitcnt lgkmcnt(0)
	v_mfma_f32_16x16x32_bf16 v[22:25], v[196:199], v[176:179], v[22:25]
	v_cvt_pk_bf16_f32 v204, v2, v3
	v_cvt_pk_bf16_f32 v205, v4, v5
	ds_write_b64 v127, v[204:205] offset:46592
	v_cvt_pk_bf16_f32 v208, v6, v7
	v_cvt_pk_bf16_f32 v209, v8, v9
	ds_write_b64 v184, v[208:209] offset:46592
	v_cvt_pk_bf16_f32 v212, v10, v11
	v_cvt_pk_bf16_f32 v213, v12, v13
	ds_write_b64 v184, v[212:213] offset:50944
	v_cvt_pk_bf16_f32 v216, v14, v15
	v_cvt_pk_bf16_f32 v217, v16, v17
	ds_write_b64 v184, v[216:217] offset:55296
	v_cvt_pk_bf16_f32 v220, v18, v19
	v_cvt_pk_bf16_f32 v221, v20, v21
	ds_write_b64 v184, v[220:221] offset:59648
	v_cvt_pk_bf16_f32 v160, v28, v29
	v_cvt_pk_bf16_f32 v161, v30, v31
	ds_write_b64 v184, v[160:161] offset:64000
	v_cvt_pk_bf16_f32 v164, v32, v33
	v_cvt_pk_bf16_f32 v165, v34, v35
	ds_write_b64 v185, v[164:165] offset:59648
	v_cvt_pk_bf16_f32 v176, v22, v23
	v_cvt_pk_bf16_f32 v177, v24, v25
	ds_write_b64 v185, v[176:177] offset:64000
	s_waitcnt vmcnt(17)
	v_mov_b32_e32 v138, v111
	s_waitcnt vmcnt(15)
	v_mov_b32_e32 v136, v113
	s_waitcnt vmcnt(13)
	v_mov_b32_e32 v135, v115
	s_waitcnt vmcnt(11)
	v_mov_b32_e32 v134, v117
	s_waitcnt vmcnt(9)
	v_mov_b32_e32 v133, v120
	s_waitcnt vmcnt(8)
	v_mov_b32_e32 v132, v121
	s_waitcnt vmcnt(7)
	v_mov_b32_e32 v45, v123
	s_waitcnt vmcnt(6)
	v_mov_b32_e32 v44, v125
	v_mov_b32_e32 v137, v112
	s_waitcnt vmcnt(4)
	v_mov_b32_e32 v47, v124
	v_mov_b32_e32 v131, v114
	v_mov_b32_e32 v130, v116
	v_mov_b32_e32 v129, v118
	s_waitcnt vmcnt(2)
	v_mov_b64_e32 v[42:43], v[38:39]
	v_mov_b32_e32 v128, v119
	v_mov_b32_e32 v127, v122
	v_mov_b32_e32 v46, v126
	v_mov_b64_e32 v[40:41], v[36:37]
	s_cbranch_scc1 .LBB0_648
